# weight transposes for the next layer deferred to after the in-proj GEMM tile loop on the slack CUs (keeps all CUs round-aligned for L2 tile sharing)
# speedup vs baseline: 1.0081x; 1.0081x over previous
; #define LAS __attribute__((address_space(3)))
; __global__ void __launch_bounds__(512) mega(Args a) {
;   extern __shared__ __attribute__((aligned(16))) char shm[];
;   LAS unsigned char* lds = (LAS unsigned char*)shm;
;   cg::grid_group grid = cg::this_grid();
;   volatile LAS unsigned* xst = (volatile LAS unsigned*)(lds + 128 * 1024);
;   if (threadIdx.x == 0) { xst[0] = 0u; xst[1] = 0u; xst[2] = 0u; xst[3] = 0u; }
;   __syncthreads();
;   const XcdBarrier xb = xcd_barrier_post((unsigned*)(a.ws + WS_BAR), xst);
_Z4mega4Args:
	v_writelane_b32 v250, 0, 30
	s_load_dwordx8 s[72:79], s[0:1], 0x60
	s_load_dwordx8 s[4:11], s[0:1], 0x40
	s_load_dword s16, s[0:1], 0x80
	s_mov_b32 s68, s2
	v_and_b32_e32 v1, 0x3ff, v0
	s_waitcnt lgkmcnt(0)
	v_writelane_b32 v252, s4, 0
	s_nop 1
	v_writelane_b32 v252, s5, 1
	v_writelane_b32 v252, s6, 2
	v_writelane_b32 v252, s7, 3
	v_writelane_b32 v252, s8, 4
	v_writelane_b32 v252, s9, 5
	v_writelane_b32 v252, s10, 6
	v_writelane_b32 v252, s11, 7
	s_add_u32 s4, s0, 0x78
	s_addc_u32 s5, s1, 0
	v_cmp_eq_u32_e64 s[6:7], 0, v1
	s_mov_b64 s[2:3], exec
	s_nop 0
	v_writelane_b32 v252, s6, 8
	s_nop 1
	v_writelane_b32 v252, s7, 9
	s_and_b64 s[6:7], s[2:3], s[6:7]
	s_mov_b64 exec, s[6:7]
	s_cbranch_execz .LBB0_2
	s_add_i32 s6, 0, 0x20000
	v_mov_b32_e32 v2, 0
	v_mov_b32_e32 v3, s6
	s_add_i32 s6, 0, 0x20004
	ds_write_b32 v3, v2
	v_mov_b32_e32 v3, s6
	s_add_i32 s6, 0, 0x20008
	ds_write_b32 v3, v2
	v_mov_b32_e32 v3, s6
	s_add_i32 s6, 0, 0x2000c
	ds_write_b32 v3, v2
	v_mov_b32_e32 v3, s6
	ds_write_b32 v3, v2

; __device__ __forceinline__ int opaque_si(int v) { asm volatile("" : "+s"(v)); return v; }
; __global__ void __launch_bounds__(512) mega(Args a) {
;     ...
;   for (int ph = a.ph_lo; ph < a.ph_hi; ++ph) {
;     if (ph > a.ph_lo) xcd_barrier(xb);
;     {
;       const int sub0 = ph > 0 ? (ph - 1) % 6 : -1, lyr = ph > 0 ? (ph - 1) / 6 + 1 : 0;
;       const int Gs = opaque_si((int)gridDim.x), cus = opaque_si((int)blockIdx.x);
;       const int nwg_in = (MT / 256) * (NIN / 256), rem = nwg_in % Gs;
;       const bool all = (ph == 0), part = (sub0 == 0 && lyr < DEPTH && rem > 0 && cus >= rem);
.LBB0_24:
	s_waitcnt vmcnt(0)
	s_barrier
	v_writelane_b32 v250, 1, 30
	s_branch .LBB0_80
.Ltd_back:
	v_writelane_b32 v250, 0, 30

; #define LAS __attribute__((address_space(3)))
; __device__ __forceinline__ int opaque_si(int v) { asm volatile("" : "+s"(v)); return v; }
; __global__ void __launch_bounds__(512) mega(Args a) {
;     ...
;       const int sub0 = ph > 0 ? (ph - 1) % 6 : -1, lyr = ph > 0 ? (ph - 1) / 6 + 1 : 0;
;       const int Gs = opaque_si((int)gridDim.x), cus = opaque_si((int)blockIdx.x);
;       const int nwg_in = (MT / 256) * (NIN / 256), rem = nwg_in % Gs;
;       const bool all = (ph == 0), part = (sub0 == 0 && lyr < DEPTH && rem > 0 && cus >= rem);
;       if ((PHMASK & 1) && (all || part)) {
;         PH_LOCALS
;         LAS float* scr = (LAS float*)(lds + wave * 16384);
;         const int gwi = all ? gw : (cu - rem) * 8 + wave, nwi = all ? NGW : (G - rem) * 8;
;     ...
;         const int it_end = (lyr + 1) * I_L;
;         for (int it = lyr * I_L + gwi; it < it_end; it += 2 * nwi) {
.LBB0_85:
	s_mov_b32 s2, s78
	s_abs_i32 s2, s2
	v_cvt_f32_u32_e32 v0, s2
	s_sub_i32 s3, 0, s2
	s_mov_b32 s9, s68
	v_rcp_iflag_f32_e32 v0, v0
	s_nop 0
	v_mul_f32_e32 v0, 0x4f7ffffe, v0
	v_cvt_u32_f32_e32 v0, v0
	s_nop 0
	v_readfirstlane_b32 s4, v0
	s_mul_i32 s3, s3, s4
	s_mul_hi_u32 s3, s4, s3
	s_add_i32 s4, s4, s3
	s_mul_hi_u32 s3, s4, 0x1180
	s_mul_i32 s3, s3, s2
	s_sub_i32 s3, 0x1180, s3
	s_sub_i32 s4, s3, s2
	s_cmp_ge_u32 s3, s2
	s_cselect_b32 s3, s4, s3
	s_sub_i32 s4, s3, s2
	s_cmp_ge_u32 s3, s2
	s_cselect_b32 s8, s4, s3
	s_cmp_eq_u32 s10, 0
	s_cselect_b64 s[4:5], -1, 0
	s_cmp_lg_u32 s10, 0
	s_cselect_b64 s[2:3], -1, 0
	s_cmp_lt_u32 s28, 4
	s_cselect_b64 s[10:11], -1, 0
	s_and_b64 s[0:1], s[0:1], s[10:11]
	s_cmp_lg_u32 s8, 0
	s_cselect_b64 s[10:11], -1, 0
	s_and_b64 s[0:1], s[0:1], s[10:11]
	s_cmp_ge_i32 s9, s8
	s_cselect_b64 s[10:11], -1, 0
	s_and_b64 s[0:1], s[10:11], s[0:1]
	v_readlane_b32 s10, v250, 30
	s_cmp_lg_u32 s10, 0
	s_cselect_b64 s[10:11], -1, 0
	s_and_b64 s[0:1], s[0:1], s[10:11]
	s_or_b64 s[0:1], s[4:5], s[0:1]
	s_andn2_b64 vcc, exec, s[0:1]
	s_cbranch_vccnz .LBB0_120
	s_and_b64 s[4:5], s[4:5], exec
	v_mov_b32_e32 v0, v225
	s_mov_b32 s0, s78
	s_mov_b32 s1, s68
	s_cselect_b32 s21, 0, s8
	s_sub_i32 s4, s1, s21
	s_lshl_b32 s4, s4, 3
	s_mul_i32 s15, s28, 0x5800
	v_ashrrev_i32_e32 v2, 6, v0
	s_add_i32 s4, s4, s15
	s_add_i32 s16, s15, 0x5800
	v_add_u32_e32 v1, s4, v2
	s_mov_b32 s9, s29
	v_cmp_gt_i32_e32 vcc, s16, v1
	s_and_saveexec_b64 s[4:5], vcc
	s_cbranch_execz .LBB0_119
	s_sub_i32 s17, s0, s21
	s_add_u32 s19, s74, s9
	v_readlane_b32 s40, v252, 0
	s_addc_u32 s20, s75, 0
	s_lshl_b64 s[22:23], s[28:29], 22
	s_lshl_b64 s[8:9], s[28:29], 24
	v_readlane_b32 s44, v252, 4
	v_readlane_b32 s45, v252, 5
	s_add_u32 s8, s44, s8
	s_addc_u32 s9, s45, s9
	s_lshl_b64 s[24:25], s[28:29], 23
	s_add_u32 s10, s19, s24
	s_addc_u32 s11, s20, s25
	s_add_u32 s10, s10, 0x14000000
	v_readlane_b32 s42, v252, 2
	s_addc_u32 s11, s11, 0
	v_readlane_b32 s43, v252, 3
	s_add_u32 s30, s42, s22
	s_addc_u32 s31, s43, s23
	s_mul_i32 s23, s28, 0xa00000
	s_mul_hi_u32 s22, s28, 0xa00000
	s_add_u32 s23, s19, s23
	s_addc_u32 s22, s20, s22
	s_add_u32 s36, s23, 0x11800000
	s_addc_u32 s37, s22, 0
	v_readlane_b32 s41, v252, 1
	s_add_u32 s38, s40, s24
	s_addc_u32 s39, s41, s25
	s_add_u32 s40, s94, s24
	s_addc_u32 s41, s95, s25
	s_mul_i32 s23, s28, 0x8c00000
	s_mul_hi_u32 s22, s28, 0x8c00000
	s_add_u32 s42, s84, s23
	s_addc_u32 s43, s85, s22
	s_mul_i32 s23, s28, 0x4600000
	s_mul_hi_u32 s22, s28, 0x4600000
	s_add_u32 s44, s19, s23
	v_bfe_u32 v26, v0, 5, 1
	v_and_b32_e32 v4, 31, v0
	v_bfe_u32 v27, v0, 3, 3
	v_lshlrev_b32_e32 v0, 3, v0
	v_lshl_add_u32 v3, v2, 14, 0
	s_addc_u32 s45, s20, s22
	v_and_b32_e32 v0, 56, v0
	s_lshl_b32 s0, s0, 3
	v_readlane_b32 s46, v252, 6
	v_readlane_b32 s47, v252, 7
	v_lshl_add_u32 v5, v4, 2, v3
	v_mul_u32_u24_e32 v6, 0x84, v26
	v_mul_u32_u24_e32 v7, 0x84, v0
	v_lshlrev_b32_e32 v8, 2, v27
	s_lshl_b32 s20, s21, 3
	v_lshl_add_u32 v32, s1, 3, v2
	s_add_i32 s0, s15, s0
	s_lshl_b32 s1, s21, 4
	v_add3_u32 v28, v3, v7, v8
	v_or_b32_e32 v29, 8, v27
	v_or_b32_e32 v30, 16, v27
	v_or_b32_e32 v31, 24, v27
	s_lshl_b32 s17, s17, 4
	s_sub_i32 s19, s15, s20
	s_sub_i32 s20, 0, s20
	s_sub_i32 s21, s0, s1
	s_mov_b64 s[46:47], 0
	v_lshlrev_b32_e32 v2, 2, v4
	v_add_u32_e32 v33, v5, v6
	s_branch .LBB0_89

; __global__ void __launch_bounds__(512) mega(Args a) {
;     ...
;         __syncthreads();
;       }
;     }
;     const int nrep = (PROBE_SUB == 6 ? ph == 0 : (ph > 0 && (ph - 1) % 6 == PROBE_SUB)) ? 2 : 1;
;     for (int rep = 0; rep < nrep; ++rep) {
;     if (rep) xcd_barrier(xb);
;     if (ph == 0) {
;     } else {
;     const int l = (ph - 1) / 6, sub = (ph - 1) % 6;
;     if ((PHMASK & 2) && sub == 0) {
.LBB0_120:
	v_readlane_b32 s0, v250, 30
	s_cmp_lg_u32 s0, 0
	s_cbranch_scc1 .Ltd_back
	s_andn2_b64 vcc, exec, s[2:3]
	s_cbranch_vccnz .LBB0_25
	v_readlane_b32 s0, v251, 55
	s_add_i32 s0, s0, -1
	s_mul_hi_i32 s1, s0, 0x2aaaaaab
	s_lshr_b32 s2, s1, 31
	s_add_i32 s2, s1, s2
	s_ashr_i32 s3, s2, 31
	s_mul_i32 s1, s2, 6
	v_writelane_b32 v251, s2, 56
	s_sub_i32 s8, s0, s1
	s_mov_b64 s[0:1], -1
	v_writelane_b32 v251, s3, 57
	v_writelane_b32 v251, s8, 58
	s_mov_b64 s[2:3], 0
	s_mov_b64 s[4:5], 0
	s_cmp_lt_i32 s8, 2
	v_writelane_b32 v251, s2, 59
	s_nop 1
	v_writelane_b32 v251, s3, 60
	s_cbranch_scc1 .LBB0_218
	v_readlane_b32 s0, v251, 58
	s_cmp_gt_i32 s0, 2
	s_cbranch_scc0 .LBB0_148
	s_cmp_gt_i32 s0, 3
	s_cbranch_scc0 .LBB0_149
	s_cmp_eq_u32 s0, 4
	s_mov_b64 s[0:1], -1
	s_cbranch_scc0 .LBB0_152
	v_mov_b32_e32 v12, v225
	s_mov_b32 s16, s78
	s_mov_b32 s17, s68
	s_mov_b32 s8, s29
	s_cmpk_gt_i32 s17, 0x1ff
	v_readfirstlane_b32 s3, v12
	s_cbranch_scc1 .LBB0_151
	s_ashr_i32 s19, s17, 31
	s_lshr_b32 s0, s19, 29
	s_add_i32 s10, s17, s0
	s_and_b32 s0, s10, -8
	s_sub_i32 s9, s17, s0
	s_cmp_gt_i32 s9, -1
	s_mov_b64 s[0:1], -1
	s_cbranch_scc0 .LBB0_128
	s_lshl_b32 s2, s9, 6
	s_mov_b64 s[0:1], 0
